# plus cross-chunk scans: next 16-chunk group prefetched (younger loads, counted waits raised)
# baseline (speedup 1.0000x reference)
; DI void chunk_scans(const Args& a, int tid) {
;     ...
;         } else { const int i3 = idx - 16384 - 8192, b = i3 >> 8, ch = i3 & 255;
;             const float* ls = (const float*)(a.ws + WS_LSUM) + ((size_t)b * NCH * 256 + ch) * 2; float* lc = (float*)(a.ws + WS_LCARRY) + (size_t)b * NCH * 256 + ch; float hv = 0.f;
; #pragma unroll 1
;             for (int c0 = 0; c0 < NCH; c0 += 16) { f32x2 t[16];
; #pragma unroll
;                 for (int j = 0; j < 16; ++j) t[j] = *(const f32x2*)(ls + (c0 + j) * 512);
; #pragma unroll
;                 for (int j = 0; j < 16; ++j) { lc[(c0 + j) * 256] = hv; hv = t[j][0] * hv + t[j][1]; } }
.LBB0_1242:
	v_lshl_add_u64 v[12:13], s[18:19], 0, v[10:11]
	s_mov_b64 s[28:29], 0x2698000
	v_lshl_add_u64 v[114:115], v[12:13], 0, s[28:29]
	v_add_co_u32_e32 v14, vcc, 0x2690000, v12
	v_lshl_add_u64 v[44:45], s[18:19], 0, v[8:9]
	s_nop 0
	v_addc_co_u32_e32 v15, vcc, 0, v13, vcc
	global_load_dwordx2 v[16:17], v[14:15], off
	s_nop 0
	global_load_dwordx2 v[14:15], v[14:15], off offset:2048
	v_add_co_u32_e32 v18, vcc, 0x2691000, v12
	s_mov_b32 s3, 0x2711000
	s_nop 0
	v_addc_co_u32_e32 v19, vcc, 0, v13, vcc
	global_load_dwordx2 v[20:21], v[18:19], off
	s_nop 0
	global_load_dwordx2 v[18:19], v[18:19], off offset:2048
	v_add_co_u32_e32 v22, vcc, 0x2692000, v12
	s_add_i32 s2, s2, 16
	s_nop 0
	v_addc_co_u32_e32 v23, vcc, 0, v13, vcc
	global_load_dwordx2 v[24:25], v[22:23], off
	s_nop 0
	global_load_dwordx2 v[22:23], v[22:23], off offset:2048
	v_add_co_u32_e32 v26, vcc, 0x2693000, v12
	s_mov_b64 s[12:13], 0x4000
	s_nop 0
	v_addc_co_u32_e32 v27, vcc, 0, v13, vcc
	global_load_dwordx2 v[28:29], v[26:27], off
	s_nop 0
	global_load_dwordx2 v[26:27], v[26:27], off offset:2048
	v_add_co_u32_e32 v30, vcc, 0x2694000, v12
	v_lshl_add_u64 v[8:9], v[8:9], 0, s[12:13]
	s_nop 0
	v_addc_co_u32_e32 v31, vcc, 0, v13, vcc
	global_load_dwordx2 v[32:33], v[30:31], off
	s_nop 0
	global_load_dwordx2 v[30:31], v[30:31], off offset:2048
	v_add_co_u32_e32 v34, vcc, 0x2695000, v12
	v_lshl_add_u64 v[10:11], v[10:11], 0, s[52:53]
	s_nop 0
	v_addc_co_u32_e32 v35, vcc, 0, v13, vcc
	global_load_dwordx2 v[36:37], v[34:35], off
	s_nop 0
	global_load_dwordx2 v[34:35], v[34:35], off offset:2048
	v_add_co_u32_e32 v38, vcc, 0x2696000, v12
	s_cmpk_lt_u32 s2, 0x70
	s_nop 0
	v_addc_co_u32_e32 v39, vcc, 0, v13, vcc
	global_load_dwordx2 v[40:41], v[38:39], off
	s_nop 0
	global_load_dwordx2 v[38:39], v[38:39], off offset:2048
	v_add_co_u32_e32 v12, vcc, 0x2697000, v12
	s_waitcnt vmcnt(13)
	v_fmac_f32_e32 v17, v0, v16
	v_addc_co_u32_e32 v13, vcc, 0, v13, vcc
	global_load_dwordx2 v[42:43], v[12:13], off
	s_nop 0
	global_load_dwordx2 v[12:13], v[12:13], off offset:2048
	v_mov_b32_e32 v110, v114
	v_mov_b32_e32 v111, v115
	s_mov_b64 s[28:29], 0x1000
	global_load_dword v112, v[110:111], off
	global_load_dword v112, v[110:111], off offset:2048
	v_lshl_add_u64 v[110:111], v[110:111], 0, s[28:29]
	global_load_dword v112, v[110:111], off
	global_load_dword v112, v[110:111], off offset:2048
	v_lshl_add_u64 v[110:111], v[110:111], 0, s[28:29]
	global_load_dword v112, v[110:111], off
	global_load_dword v112, v[110:111], off offset:2048
	v_lshl_add_u64 v[110:111], v[110:111], 0, s[28:29]
	global_load_dword v112, v[110:111], off
	global_load_dword v112, v[110:111], off offset:2048
	v_lshl_add_u64 v[110:111], v[110:111], 0, s[28:29]
	global_load_dword v112, v[110:111], off
	global_load_dword v112, v[110:111], off offset:2048
	v_lshl_add_u64 v[110:111], v[110:111], 0, s[28:29]
	global_load_dword v112, v[110:111], off
	global_load_dword v112, v[110:111], off offset:2048
	v_lshl_add_u64 v[110:111], v[110:111], 0, s[28:29]
	global_load_dword v112, v[110:111], off
	global_load_dword v112, v[110:111], off offset:2048
	v_lshl_add_u64 v[110:111], v[110:111], 0, s[28:29]
	global_load_dword v112, v[110:111], off
	global_load_dword v112, v[110:111], off offset:2048
	s_waitcnt vmcnt(30)
	v_fmac_f32_e32 v15, v14, v17
	v_add_co_u32_e32 v46, vcc, 0x2710000, v44
	s_waitcnt vmcnt(29)
	v_fmac_f32_e32 v21, v20, v15
	s_waitcnt vmcnt(28)
	v_fmac_f32_e32 v19, v18, v21
	v_addc_co_u32_e32 v47, vcc, 0, v45, vcc
	v_add_co_u32_e32 v14, vcc, s3, v44
	s_waitcnt vmcnt(27)
	v_fmac_f32_e32 v25, v24, v19
	s_waitcnt vmcnt(26)
	v_fmac_f32_e32 v23, v22, v25
	global_store_dword v[46:47], v15, off offset:2048
	v_addc_co_u32_e32 v15, vcc, 0, v45, vcc
	s_waitcnt vmcnt(26)
	v_fmac_f32_e32 v29, v28, v23
	s_waitcnt vmcnt(25)
	v_fmac_f32_e32 v27, v26, v29
	s_mov_b32 s3, 0x2712000
	v_add_co_u32_e32 v16, vcc, s3, v44
	global_store_dword v[46:47], v17, off offset:1024
	s_waitcnt vmcnt(25)
	v_fmac_f32_e32 v33, v32, v27
	s_waitcnt vmcnt(24)
	v_fmac_f32_e32 v31, v30, v33
	v_addc_co_u32_e32 v17, vcc, 0, v45, vcc
	s_mov_b32 s3, 0x2713000
	global_store_dword v[14:15], v25, off offset:1024
	s_waitcnt vmcnt(24)
	v_fmac_f32_e32 v37, v36, v31
	s_waitcnt vmcnt(23)
	v_fmac_f32_e32 v35, v34, v37
	global_store_dword v[14:15], v23, off offset:2048
	global_store_dword v[14:15], v29, off offset:3072
	v_add_co_u32_e32 v14, vcc, s3, v44
	s_waitcnt vmcnt(24)
	v_fmac_f32_e32 v41, v40, v35
	s_waitcnt vmcnt(23)
	v_fmac_f32_e32 v39, v38, v41
	global_store_dword v[46:47], v0, off
	v_addc_co_u32_e32 v15, vcc, 0, v45, vcc
	global_store_dword v[46:47], v21, off offset:3072
	global_store_dword v[16:17], v19, off offset:-4096
	global_store_dword v[16:17], v27, off
	global_store_dword v[16:17], v33, off offset:1024
	global_store_dword v[16:17], v31, off offset:2048
	global_store_dword v[16:17], v37, off offset:3072
	global_store_dword v[14:15], v35, off
	global_store_dword v[14:15], v41, off offset:1024
	global_store_dword v[14:15], v39, off offset:2048
	s_waitcnt vmcnt(32)
	v_fmac_f32_e32 v43, v42, v39
	s_waitcnt vmcnt(31)
	v_fmac_f32_e32 v13, v12, v43
	v_mov_b32_e32 v0, v13
	global_store_dword v[14:15], v43, off offset:3072
	s_cbranch_scc1 .LBB0_1242

; DI unsigned pk2(float lo, float hi) { const f32x2 v = {lo, hi}; const hwbf16x2 b = __builtin_convertvector(v, hwbf16x2); return __builtin_bit_cast(unsigned, b); }
; DI f32x4 bf4_to_f32(const u32x2 v) { return (f32x4){__uint_as_float(v.x << 16), __uint_as_float(v.x & 0xffff0000u), __uint_as_float(v.y << 16), __uint_as_float(v.y & 0xffff0000u)}; }
; DI float ret_lg(int h) { return log1pf(-exp2f(-5.0f - (float)h)); }
; DI void chunk_scans(const Args& a, int tid) {
;     ...
;         } else if (idx < 16384 + 8192) { const int i2 = idx - 16384, b = i2 >> 12, rem = (i2 & 4095) * 4, h = rem >> 12; const float cd = __expf(ret_lg(h) * 128.0f);
;             bf16_t* p = (bf16_t*)((unsigned char*)a.out + DO_RS) + (size_t)b * NCH * 16384 + rem; f32x4 st = {0.f, 0.f, 0.f, 0.f};
; #pragma unroll 1
;             for (int c0 = 0; c0 < NCH; c0 += 16) { u32x2 t[16];
; #pragma unroll
;                 for (int j = 0; j < 16; ++j) t[j] = *(const u32x2*)(p + (size_t)(c0 + j) * 16384);
; #pragma unroll
;                 for (int j = 0; j < 16; ++j) { u32x2 w; w.x = pk2(st[0], st[1]); w.y = pk2(st[2], st[3]); *(u32x2*)(p + (size_t)(c0 + j) * 16384) = w; st = st * cd + bf4_to_f32(t[j]); } }
.LBB0_1245:
	v_add_co_u32_e32 v18, vcc, 0x8000, v10
	global_load_dwordx2 v[20:21], v[10:11], off
	s_nop 0
	v_addc_co_u32_e32 v19, vcc, 0, v11, vcc
	v_add_co_u32_e32 v50, vcc, 0x10000, v10
	s_mov_b32 s2, 0x60000
	s_nop 0
	v_addc_co_u32_e32 v51, vcc, 0, v11, vcc
	v_add_co_u32_e32 v44, vcc, 0x18000, v10
	global_load_dwordx2 v[70:71], v[18:19], off
	global_load_dwordx2 v[62:63], v[50:51], off
	v_addc_co_u32_e32 v45, vcc, 0, v11, vcc
	v_add_co_u32_e32 v42, vcc, 0x20000, v10
	v_cvt_pk_bf16_f32 v54, v14, v15
	s_nop 0
	v_addc_co_u32_e32 v43, vcc, 0, v11, vcc
	v_add_co_u32_e32 v36, vcc, 0x28000, v10
	global_load_dwordx2 v[60:61], v[44:45], off
	global_load_dwordx2 v[56:57], v[42:43], off
	v_addc_co_u32_e32 v37, vcc, 0, v11, vcc
	v_add_co_u32_e32 v34, vcc, 0x30000, v10
	v_cvt_pk_bf16_f32 v55, v16, v17
	s_nop 0
	v_addc_co_u32_e32 v35, vcc, 0, v11, vcc
	v_add_co_u32_e32 v30, vcc, 0x38000, v10
	global_load_dwordx2 v[52:53], v[36:37], off
	global_load_dwordx2 v[48:49], v[34:35], off
	v_addc_co_u32_e32 v31, vcc, 0, v11, vcc
	v_add_co_u32_e32 v28, vcc, 0x40000, v10
	s_add_i32 s12, s12, 16
	s_nop 0
	v_addc_co_u32_e32 v29, vcc, 0, v11, vcc
	v_add_co_u32_e32 v26, vcc, 0x48000, v10
	global_load_dwordx2 v[46:47], v[30:31], off
	global_load_dwordx2 v[40:41], v[28:29], off
	v_addc_co_u32_e32 v27, vcc, 0, v11, vcc
	v_add_co_u32_e32 v24, vcc, 0x50000, v10
	s_cmpk_gt_u32 s12, 0x6f
	s_nop 0
	v_addc_co_u32_e32 v25, vcc, 0, v11, vcc
	v_add_co_u32_e32 v22, vcc, 0x58000, v10
	global_load_dwordx2 v[38:39], v[26:27], off
	global_load_dwordx2 v[32:33], v[24:25], off
	v_addc_co_u32_e32 v23, vcc, 0, v11, vcc
	v_add_co_u32_e32 v64, vcc, s2, v10
	s_mov_b32 s2, 0x70000
	s_nop 0
	v_addc_co_u32_e32 v65, vcc, 0, v11, vcc
	v_add_co_u32_e32 v58, vcc, 0x68000, v10
	global_load_dwordx2 v[80:81], v[22:23], off
	global_load_dwordx2 v[74:75], v[64:65], off
	v_addc_co_u32_e32 v59, vcc, 0, v11, vcc
	v_add_co_u32_e32 v68, vcc, s2, v10
	global_load_dwordx2 v[78:79], v[58:59], off
	s_nop 0
	v_addc_co_u32_e32 v69, vcc, 0, v11, vcc
	v_add_co_u32_e32 v66, vcc, 0x78000, v10
	s_mov_b64 s[2:3], 0x80000
	s_nop 0
	v_addc_co_u32_e32 v67, vcc, 0, v11, vcc
	global_load_dwordx2 v[76:77], v[68:69], off
	global_load_dwordx2 v[72:73], v[66:67], off
	s_mov_b64 s[28:29], 0x80000
	v_lshl_add_u64 v[110:111], v[10:11], 0, s[28:29]
	s_mov_b64 s[28:29], 0x8000
	global_load_dword v112, v[110:111], off
	v_lshl_add_u64 v[110:111], v[110:111], 0, s[28:29]
	global_load_dword v112, v[110:111], off
	v_lshl_add_u64 v[110:111], v[110:111], 0, s[28:29]
	global_load_dword v112, v[110:111], off
	v_lshl_add_u64 v[110:111], v[110:111], 0, s[28:29]
	global_load_dword v112, v[110:111], off
	v_lshl_add_u64 v[110:111], v[110:111], 0, s[28:29]
	global_load_dword v112, v[110:111], off
	v_lshl_add_u64 v[110:111], v[110:111], 0, s[28:29]
	global_load_dword v112, v[110:111], off
	v_lshl_add_u64 v[110:111], v[110:111], 0, s[28:29]
	global_load_dword v112, v[110:111], off
	v_lshl_add_u64 v[110:111], v[110:111], 0, s[28:29]
	global_load_dword v112, v[110:111], off
	v_lshl_add_u64 v[110:111], v[110:111], 0, s[28:29]
	global_load_dword v112, v[110:111], off
	v_lshl_add_u64 v[110:111], v[110:111], 0, s[28:29]
	global_load_dword v112, v[110:111], off
	v_lshl_add_u64 v[110:111], v[110:111], 0, s[28:29]
	global_load_dword v112, v[110:111], off
	v_lshl_add_u64 v[110:111], v[110:111], 0, s[28:29]
	global_load_dword v112, v[110:111], off
	v_lshl_add_u64 v[110:111], v[110:111], 0, s[28:29]
	global_load_dword v112, v[110:111], off
	v_lshl_add_u64 v[110:111], v[110:111], 0, s[28:29]
	global_load_dword v112, v[110:111], off
	v_lshl_add_u64 v[110:111], v[110:111], 0, s[28:29]
	global_load_dword v112, v[110:111], off
	v_lshl_add_u64 v[110:111], v[110:111], 0, s[28:29]
	global_load_dword v112, v[110:111], off
	s_nop 0
	global_store_dwordx2 v[10:11], v[54:55], off
	v_lshl_add_u64 v[10:11], v[10:11], 0, s[2:3]
	s_waitcnt vmcnt(32)
	v_lshlrev_b32_e32 v54, 16, v20
	v_and_b32_e32 v55, 0xffff0000, v20
	v_lshlrev_b32_e32 v20, 16, v21
	v_and_b32_e32 v21, 0xffff0000, v21
	v_pk_fma_f32 v[16:17], v[12:13], v[16:17], v[20:21]
	v_pk_fma_f32 v[14:15], v[8:9], v[14:15], v[54:55]
	v_cvt_pk_bf16_f32 v21, v16, v17
	v_cvt_pk_bf16_f32 v20, v14, v15
	global_store_dwordx2 v[18:19], v[20:21], off
	s_waitcnt vmcnt(32)
	v_lshlrev_b32_e32 v54, 16, v70
	v_and_b32_e32 v55, 0xffff0000, v70
	v_lshlrev_b32_e32 v70, 16, v71
	v_and_b32_e32 v71, 0xffff0000, v71
	v_pk_fma_f32 v[16:17], v[12:13], v[16:17], v[70:71]
	v_pk_fma_f32 v[14:15], v[8:9], v[14:15], v[54:55]
	s_waitcnt vmcnt(31)
	v_lshlrev_b32_e32 v18, 16, v62
	v_and_b32_e32 v19, 0xffff0000, v62
	v_lshlrev_b32_e32 v20, 16, v63
	v_and_b32_e32 v21, 0xffff0000, v63
	v_cvt_pk_bf16_f32 v54, v14, v15
	v_cvt_pk_bf16_f32 v55, v16, v17
	v_pk_fma_f32 v[16:17], v[12:13], v[16:17], v[20:21]
	v_pk_fma_f32 v[14:15], v[8:9], v[14:15], v[18:19]
	s_waitcnt vmcnt(30)
; DI unsigned pk2(float lo, float hi) { const f32x2 v = {lo, hi}; const hwbf16x2 b = __builtin_convertvector(v, hwbf16x2); return __builtin_bit_cast(unsigned, b); }
; DI f32x4 bf4_to_f32(const u32x2 v) { return (f32x4){__uint_as_float(v.x << 16), __uint_as_float(v.x & 0xffff0000u), __uint_as_float(v.y << 16), __uint_as_float(v.y & 0xffff0000u)}; }
; DI void chunk_scans(const Args& a, int tid) {
;     ...
;             for (int c0 = 0; c0 < NCH; c0 += 16) { u32x2 t[16];
; #pragma unroll
;                 for (int j = 0; j < 16; ++j) t[j] = *(const u32x2*)(p + (size_t)(c0 + j) * 16384);
; #pragma unroll
;                 for (int j = 0; j < 16; ++j) { u32x2 w; w.x = pk2(st[0], st[1]); w.y = pk2(st[2], st[3]); *(u32x2*)(p + (size_t)(c0 + j) * 16384) = w; st = st * cd + bf4_to_f32(t[j]); } }
	v_lshlrev_b32_e32 v18, 16, v60
	v_and_b32_e32 v19, 0xffff0000, v60
	v_lshlrev_b32_e32 v20, 16, v61
	v_and_b32_e32 v21, 0xffff0000, v61
	global_store_dwordx2 v[50:51], v[54:55], off
	v_cvt_pk_bf16_f32 v50, v14, v15
	v_cvt_pk_bf16_f32 v51, v16, v17
	v_pk_fma_f32 v[16:17], v[12:13], v[16:17], v[20:21]
	v_pk_fma_f32 v[14:15], v[8:9], v[14:15], v[18:19]
	s_waitcnt vmcnt(30)
	v_lshlrev_b32_e32 v18, 16, v56
	v_and_b32_e32 v19, 0xffff0000, v56
	v_lshlrev_b32_e32 v20, 16, v57
	v_and_b32_e32 v21, 0xffff0000, v57
	global_store_dwordx2 v[44:45], v[50:51], off
	v_cvt_pk_bf16_f32 v44, v14, v15
	v_cvt_pk_bf16_f32 v45, v16, v17
	v_pk_fma_f32 v[16:17], v[12:13], v[16:17], v[20:21]
	v_pk_fma_f32 v[14:15], v[8:9], v[14:15], v[18:19]
	s_waitcnt vmcnt(30)
	v_lshlrev_b32_e32 v18, 16, v52
	v_and_b32_e32 v19, 0xffff0000, v52
	v_lshlrev_b32_e32 v20, 16, v53
	v_and_b32_e32 v21, 0xffff0000, v53
	global_store_dwordx2 v[42:43], v[44:45], off
	v_cvt_pk_bf16_f32 v42, v14, v15
	v_cvt_pk_bf16_f32 v43, v16, v17
	v_pk_fma_f32 v[16:17], v[12:13], v[16:17], v[20:21]
	v_pk_fma_f32 v[14:15], v[8:9], v[14:15], v[18:19]
	s_waitcnt vmcnt(30)
	v_lshlrev_b32_e32 v18, 16, v48
	v_and_b32_e32 v19, 0xffff0000, v48
	v_lshlrev_b32_e32 v20, 16, v49
	v_and_b32_e32 v21, 0xffff0000, v49
	global_store_dwordx2 v[36:37], v[42:43], off
	v_cvt_pk_bf16_f32 v36, v14, v15
	v_cvt_pk_bf16_f32 v37, v16, v17
	v_pk_fma_f32 v[16:17], v[12:13], v[16:17], v[20:21]
	v_pk_fma_f32 v[14:15], v[8:9], v[14:15], v[18:19]
	s_waitcnt vmcnt(30)
	v_lshlrev_b32_e32 v18, 16, v46
	v_and_b32_e32 v19, 0xffff0000, v46
	v_lshlrev_b32_e32 v20, 16, v47
	v_and_b32_e32 v21, 0xffff0000, v47
	global_store_dwordx2 v[34:35], v[36:37], off
	v_cvt_pk_bf16_f32 v34, v14, v15
	v_cvt_pk_bf16_f32 v35, v16, v17
	v_pk_fma_f32 v[16:17], v[12:13], v[16:17], v[20:21]
	v_pk_fma_f32 v[14:15], v[8:9], v[14:15], v[18:19]
	s_waitcnt vmcnt(30)
	v_lshlrev_b32_e32 v18, 16, v40
	v_and_b32_e32 v19, 0xffff0000, v40
	v_lshlrev_b32_e32 v20, 16, v41
	v_and_b32_e32 v21, 0xffff0000, v41
	global_store_dwordx2 v[30:31], v[34:35], off
	v_cvt_pk_bf16_f32 v30, v14, v15
	v_cvt_pk_bf16_f32 v31, v16, v17
	v_pk_fma_f32 v[16:17], v[12:13], v[16:17], v[20:21]
	v_pk_fma_f32 v[14:15], v[8:9], v[14:15], v[18:19]
	s_waitcnt vmcnt(30)
	v_lshlrev_b32_e32 v18, 16, v38
	v_and_b32_e32 v19, 0xffff0000, v38
	v_lshlrev_b32_e32 v20, 16, v39
	v_and_b32_e32 v21, 0xffff0000, v39
	global_store_dwordx2 v[28:29], v[30:31], off
	v_cvt_pk_bf16_f32 v28, v14, v15
	v_cvt_pk_bf16_f32 v29, v16, v17
	v_pk_fma_f32 v[16:17], v[12:13], v[16:17], v[20:21]
	v_pk_fma_f32 v[14:15], v[8:9], v[14:15], v[18:19]
	s_waitcnt vmcnt(30)
	v_lshlrev_b32_e32 v18, 16, v32
	v_and_b32_e32 v19, 0xffff0000, v32
	v_lshlrev_b32_e32 v20, 16, v33
	v_and_b32_e32 v21, 0xffff0000, v33
	global_store_dwordx2 v[26:27], v[28:29], off
	v_cvt_pk_bf16_f32 v26, v14, v15
	v_cvt_pk_bf16_f32 v27, v16, v17
	v_pk_fma_f32 v[16:17], v[12:13], v[16:17], v[20:21]
	v_pk_fma_f32 v[14:15], v[8:9], v[14:15], v[18:19]
	s_waitcnt vmcnt(30)
	v_lshlrev_b32_e32 v18, 16, v80
	v_and_b32_e32 v19, 0xffff0000, v80
	v_lshlrev_b32_e32 v20, 16, v81
	v_and_b32_e32 v21, 0xffff0000, v81
	global_store_dwordx2 v[24:25], v[26:27], off
	v_cvt_pk_bf16_f32 v24, v14, v15
	v_cvt_pk_bf16_f32 v25, v16, v17
	v_pk_fma_f32 v[16:17], v[12:13], v[16:17], v[20:21]
	v_pk_fma_f32 v[14:15], v[8:9], v[14:15], v[18:19]
	s_waitcnt vmcnt(30)
	v_lshlrev_b32_e32 v18, 16, v74
	v_and_b32_e32 v19, 0xffff0000, v74
	v_lshlrev_b32_e32 v20, 16, v75
	v_and_b32_e32 v21, 0xffff0000, v75
	global_store_dwordx2 v[22:23], v[24:25], off
	v_cvt_pk_bf16_f32 v22, v14, v15
	v_cvt_pk_bf16_f32 v23, v16, v17
	v_pk_fma_f32 v[16:17], v[12:13], v[16:17], v[20:21]
	v_pk_fma_f32 v[14:15], v[8:9], v[14:15], v[18:19]
	s_waitcnt vmcnt(30)
	v_lshlrev_b32_e32 v18, 16, v78
	v_and_b32_e32 v19, 0xffff0000, v78
	v_lshlrev_b32_e32 v20, 16, v79
	v_and_b32_e32 v21, 0xffff0000, v79
	global_store_dwordx2 v[64:65], v[22:23], off
	v_cvt_pk_bf16_f32 v22, v14, v15
	v_cvt_pk_bf16_f32 v23, v16, v17
	v_pk_fma_f32 v[16:17], v[12:13], v[16:17], v[20:21]
	v_pk_fma_f32 v[14:15], v[8:9], v[14:15], v[18:19]
	s_waitcnt vmcnt(30)
	v_lshlrev_b32_e32 v18, 16, v76
	v_and_b32_e32 v19, 0xffff0000, v76
	v_lshlrev_b32_e32 v20, 16, v77
	v_and_b32_e32 v21, 0xffff0000, v77
	global_store_dwordx2 v[58:59], v[22:23], off
	v_cvt_pk_bf16_f32 v22, v14, v15
	v_cvt_pk_bf16_f32 v23, v16, v17
	v_pk_fma_f32 v[16:17], v[12:13], v[16:17], v[20:21]
	v_pk_fma_f32 v[14:15], v[8:9], v[14:15], v[18:19]
	s_waitcnt vmcnt(30)
	v_lshlrev_b32_e32 v18, 16, v72
	v_and_b32_e32 v19, 0xffff0000, v72
	v_lshlrev_b32_e32 v20, 16, v73
	v_and_b32_e32 v21, 0xffff0000, v73
	global_store_dwordx2 v[68:69], v[22:23], off
	v_cvt_pk_bf16_f32 v22, v14, v15
	v_cvt_pk_bf16_f32 v23, v16, v17
	v_pk_fma_f32 v[16:17], v[12:13], v[16:17], v[20:21]
	v_pk_fma_f32 v[14:15], v[8:9], v[14:15], v[18:19]
	global_store_dwordx2 v[66:67], v[22:23], off
	s_cbranch_scc0 .LBB0_1245

; DI unsigned pk2(float lo, float hi) { const f32x2 v = {lo, hi}; const hwbf16x2 b = __builtin_convertvector(v, hwbf16x2); return __builtin_bit_cast(unsigned, b); }
; DI f32x4 bf4_to_f32(const u32x2 v) { return (f32x4){__uint_as_float(v.x << 16), __uint_as_float(v.x & 0xffff0000u), __uint_as_float(v.y << 16), __uint_as_float(v.y & 0xffff0000u)}; }
; DI void chunk_scans(const Args& a, int tid) {
;     ...
;         if (idx < 16384) { const int b = idx >> 13, rem = (idx & 8191) * 4, h = rem >> 13;
;             bf16_t* p = (bf16_t*)((unsigned char*)a.out + DO_ST) + (size_t)b * NCH * 32768 + rem; const float* dec = (const float*)(a.ws + WS_SDEC) + b * NCH * 4 + h; f32x4 st = {0.f, 0.f, 0.f, 0.f};
; #pragma unroll 1
;             for (int c0 = 0; c0 < NCH; c0 += 16) { u32x2 t[16]; float d[16];
; #pragma unroll
;                 for (int j = 0; j < 16; ++j) { t[j] = *(const u32x2*)(p + (size_t)(c0 + j) * 32768); d[j] = dec[(c0 + j) * 4]; }
; #pragma unroll
;                 for (int j = 0; j < 16; ++j) { u32x2 w; w.x = pk2(st[0], st[1]); w.y = pk2(st[2], st[3]); *(u32x2*)(p + (size_t)(c0 + j) * 32768) = w; st = st * d[j] + bf4_to_f32(t[j]); } }
.LBB0_1249:
	v_add_co_u32_e32 v20, vcc, 0xfff10000, v10
	global_load_dword v24, v[8:9], off offset:-240
	global_load_dword v26, v[8:9], off offset:-224
	v_addc_co_u32_e32 v21, vcc, -1, v11, vcc
	v_add_co_u32_e32 v22, vcc, 0xfff20000, v10
	s_mov_b32 s13, 0xffff0000
	s_nop 0
	v_addc_co_u32_e32 v23, vcc, -1, v11, vcc
	v_add_co_u32_e32 v28, vcc, 0xfff30000, v10
	v_cvt_pk_bf16_f32 v108, v16, v17
	s_nop 0
	v_addc_co_u32_e32 v29, vcc, -1, v11, vcc
	v_add_co_u32_e32 v30, vcc, 0xfff40000, v10
	v_cvt_pk_bf16_f32 v109, v18, v19
	s_nop 0
	v_addc_co_u32_e32 v31, vcc, -1, v11, vcc
	global_load_dwordx2 v[32:33], v[20:21], off
	global_load_dwordx2 v[34:35], v[22:23], off
	global_load_dwordx2 v[36:37], v[28:29], off
	global_load_dwordx2 v[38:39], v[30:31], off
	v_add_co_u32_e32 v40, vcc, 0xfff50000, v10
	s_add_i32 s12, s12, 16
	s_nop 0
	v_addc_co_u32_e32 v41, vcc, -1, v11, vcc
	v_add_co_u32_e32 v42, vcc, 0xfff60000, v10
	s_mov_b64 s[14:15], 0x100
	s_nop 0
	v_addc_co_u32_e32 v43, vcc, -1, v11, vcc
	v_add_co_u32_e32 v44, vcc, 0xfff70000, v10
	s_cmpk_gt_u32 s12, 0x6f
	s_nop 0
	v_addc_co_u32_e32 v45, vcc, -1, v11, vcc
	v_add_co_u32_e32 v46, vcc, 0xfff80000, v10
	s_nop 1
	v_addc_co_u32_e32 v47, vcc, -1, v11, vcc
	global_load_dwordx2 v[48:49], v[40:41], off
	global_load_dwordx2 v[50:51], v[42:43], off
	global_load_dwordx2 v[52:53], v[44:45], off
	global_load_dwordx2 v[54:55], v[46:47], off
	global_load_dword v56, v[8:9], off offset:-208
	global_load_dword v58, v[8:9], off offset:-192
	global_load_dword v60, v[8:9], off offset:-176
	global_load_dword v62, v[8:9], off offset:-160
	global_load_dword v64, v[8:9], off offset:-144
	global_load_dword v66, v[8:9], off offset:-128
	v_add_co_u32_e32 v68, vcc, 0xfff90000, v10
	s_nop 1
	v_addc_co_u32_e32 v69, vcc, -1, v11, vcc
	v_add_co_u32_e32 v70, vcc, 0xfffa0000, v10
	s_nop 1
	v_addc_co_u32_e32 v71, vcc, -1, v11, vcc
	v_add_co_u32_e32 v72, vcc, 0xfffb0000, v10
	s_nop 1
	v_addc_co_u32_e32 v73, vcc, -1, v11, vcc
	v_add_co_u32_e32 v74, vcc, 0xfffc0000, v10
	s_nop 1
	v_addc_co_u32_e32 v75, vcc, -1, v11, vcc
	global_load_dwordx2 v[76:77], v[68:69], off
	global_load_dwordx2 v[78:79], v[70:71], off
	global_load_dwordx2 v[80:81], v[72:73], off
	global_load_dwordx2 v[82:83], v[74:75], off
	v_add_co_u32_e32 v84, vcc, 0xfffd0000, v10
	s_nop 1
	v_addc_co_u32_e32 v85, vcc, -1, v11, vcc
	v_add_co_u32_e32 v86, vcc, 0xfffe0000, v10
	s_nop 1
	v_addc_co_u32_e32 v87, vcc, -1, v11, vcc
	v_add_co_u32_e32 v14, vcc, s13, v10
	s_nop 1
	v_addc_co_u32_e32 v15, vcc, -1, v11, vcc
	global_load_dwordx2 v[88:89], v[84:85], off
	global_load_dwordx2 v[90:91], v[86:87], off
	global_load_dwordx2 v[92:93], v[14:15], off
	global_load_dwordx2 v[12:13], v[10:11], off
	global_load_dword v94, v[8:9], off offset:-112
	global_load_dword v96, v[8:9], off offset:-96
	global_load_dword v98, v[8:9], off offset:-80
	global_load_dword v100, v[8:9], off offset:-64
	global_load_dword v102, v[8:9], off offset:-48
	global_load_dword v104, v[8:9], off offset:-32
	global_load_dword v106, v[8:9], off offset:-16
	global_load_dword v0, v[8:9], off
	s_mov_b64 s[28:29], 0x10000
	v_lshl_add_u64 v[110:111], v[10:11], 0, s[28:29]
	global_load_dword v112, v[110:111], off
	v_lshl_add_u64 v[110:111], v[110:111], 0, s[28:29]
	global_load_dword v112, v[110:111], off
	v_lshl_add_u64 v[110:111], v[110:111], 0, s[28:29]
	global_load_dword v112, v[110:111], off
	v_lshl_add_u64 v[110:111], v[110:111], 0, s[28:29]
	global_load_dword v112, v[110:111], off
	v_lshl_add_u64 v[110:111], v[110:111], 0, s[28:29]
	global_load_dword v112, v[110:111], off
	v_lshl_add_u64 v[110:111], v[110:111], 0, s[28:29]
	global_load_dword v112, v[110:111], off
	v_lshl_add_u64 v[110:111], v[110:111], 0, s[28:29]
	global_load_dword v112, v[110:111], off
	v_lshl_add_u64 v[110:111], v[110:111], 0, s[28:29]
	global_load_dword v112, v[110:111], off
	v_lshl_add_u64 v[110:111], v[110:111], 0, s[28:29]
	global_load_dword v112, v[110:111], off
	v_lshl_add_u64 v[110:111], v[110:111], 0, s[28:29]
	global_load_dword v112, v[110:111], off
	v_lshl_add_u64 v[110:111], v[110:111], 0, s[28:29]
	global_load_dword v112, v[110:111], off
	v_lshl_add_u64 v[110:111], v[110:111], 0, s[28:29]
	global_load_dword v112, v[110:111], off
	v_lshl_add_u64 v[110:111], v[110:111], 0, s[28:29]
	global_load_dword v112, v[110:111], off
	v_lshl_add_u64 v[110:111], v[110:111], 0, s[28:29]
	global_load_dword v112, v[110:111], off
	v_lshl_add_u64 v[110:111], v[110:111], 0, s[28:29]
	global_load_dword v112, v[110:111], off
	v_lshl_add_u64 v[110:111], v[110:111], 0, s[28:29]
	global_load_dword v112, v[110:111], off
	v_lshl_add_u64 v[8:9], v[8:9], 0, s[14:15]
	global_store_dwordx2 v[20:21], v[108:109], off
	s_waitcnt vmcnt(46)
	v_lshlrev_b32_e32 v20, 16, v32
	v_and_b32_e32 v21, 0xffff0000, v32
	v_lshlrev_b32_e32 v32, 16, v33
	v_and_b32_e32 v33, 0xffff0000, v33
	v_pk_fma_f32 v[18:19], v[18:19], v[24:25], v[32:33] op_sel_hi:[1,0,1]
	v_pk_fma_f32 v[16:17], v[16:17], v[24:25], v[20:21] op_sel_hi:[1,0,1]
	v_cvt_pk_bf16_f32 v21, v18, v19
	v_cvt_pk_bf16_f32 v20, v16, v17
	global_store_dwordx2 v[22:23], v[20:21], off
	s_waitcnt vmcnt(46)
	v_lshlrev_b32_e32 v20, 16, v34
	v_and_b32_e32 v21, 0xffff0000, v34
	v_lshlrev_b32_e32 v22, 16, v35
	v_and_b32_e32 v23, 0xffff0000, v35
	v_pk_fma_f32 v[18:19], v[26:27], v[18:19], v[22:23] op_sel_hi:[0,1,1]
	v_pk_fma_f32 v[16:17], v[26:27], v[16:17], v[20:21] op_sel_hi:[0,1,1]
	v_cvt_pk_bf16_f32 v20, v16, v17
	v_cvt_pk_bf16_f32 v21, v18, v19
	global_store_dwordx2 v[28:29], v[20:21], off
	s_waitcnt vmcnt(46)
	v_lshlrev_b32_e32 v20, 16, v36
	v_and_b32_e32 v21, 0xffff0000, v36
	v_lshlrev_b32_e32 v22, 16, v37
	v_and_b32_e32 v23, 0xffff0000, v37
	s_waitcnt vmcnt(40)
	v_pk_fma_f32 v[18:19], v[56:57], v[18:19], v[22:23] op_sel_hi:[0,1,1]
	v_pk_fma_f32 v[16:17], v[56:57], v[16:17], v[20:21] op_sel_hi:[0,1,1]
	v_cvt_pk_bf16_f32 v20, v16, v17
	v_cvt_pk_bf16_f32 v21, v18, v19
	global_store_dwordx2 v[30:31], v[20:21], off
	v_lshlrev_b32_e32 v20, 16, v38
	v_and_b32_e32 v21, 0xffff0000, v38
	v_lshlrev_b32_e32 v22, 16, v39
	v_and_b32_e32 v23, 0xffff0000, v39
	s_waitcnt vmcnt(40)
	v_pk_fma_f32 v[18:19], v[58:59], v[18:19], v[22:23] op_sel_hi:[0,1,1]
	v_pk_fma_f32 v[16:17], v[58:59], v[16:17], v[20:21] op_sel_hi:[0,1,1]
	v_cvt_pk_bf16_f32 v20, v16, v17
	v_cvt_pk_bf16_f32 v21, v18, v19
	global_store_dwordx2 v[40:41], v[20:21], off
	v_lshlrev_b32_e32 v20, 16, v48
	v_and_b32_e32 v21, 0xffff0000, v48
	v_lshlrev_b32_e32 v22, 16, v49
	v_and_b32_e32 v23, 0xffff0000, v49
	s_waitcnt vmcnt(40)
	v_pk_fma_f32 v[18:19], v[60:61], v[18:19], v[22:23] op_sel_hi:[0,1,1]
	v_pk_fma_f32 v[16:17], v[60:61], v[16:17], v[20:21] op_sel_hi:[0,1,1]
	v_cvt_pk_bf16_f32 v20, v16, v17
	v_cvt_pk_bf16_f32 v21, v18, v19
	global_store_dwordx2 v[42:43], v[20:21], off
	v_lshlrev_b32_e32 v20, 16, v50
	v_and_b32_e32 v21, 0xffff0000, v50
	v_lshlrev_b32_e32 v22, 16, v51
	v_and_b32_e32 v23, 0xffff0000, v51
	s_waitcnt vmcnt(40)
	v_pk_fma_f32 v[18:19], v[62:63], v[18:19], v[22:23] op_sel_hi:[0,1,1]
	v_pk_fma_f32 v[16:17], v[62:63], v[16:17], v[20:21] op_sel_hi:[0,1,1]
	v_cvt_pk_bf16_f32 v20, v16, v17
	v_cvt_pk_bf16_f32 v21, v18, v19
	global_store_dwordx2 v[44:45], v[20:21], off
	v_lshlrev_b32_e32 v20, 16, v52
	v_and_b32_e32 v21, 0xffff0000, v52
	v_lshlrev_b32_e32 v22, 16, v53
	v_and_b32_e32 v23, 0xffff0000, v53
	s_waitcnt vmcnt(40)
	v_pk_fma_f32 v[18:19], v[64:65], v[18:19], v[22:23] op_sel_hi:[0,1,1]
	v_pk_fma_f32 v[16:17], v[64:65], v[16:17], v[20:21] op_sel_hi:[0,1,1]
	v_cvt_pk_bf16_f32 v20, v16, v17
	v_cvt_pk_bf16_f32 v21, v18, v19
	global_store_dwordx2 v[46:47], v[20:21], off
	v_lshlrev_b32_e32 v20, 16, v54
	v_and_b32_e32 v21, 0xffff0000, v54
	v_lshlrev_b32_e32 v22, 16, v55
	v_and_b32_e32 v23, 0xffff0000, v55
	s_waitcnt vmcnt(40)
	v_pk_fma_f32 v[18:19], v[66:67], v[18:19], v[22:23] op_sel_hi:[0,1,1]
	v_pk_fma_f32 v[16:17], v[66:67], v[16:17], v[20:21] op_sel_hi:[0,1,1]
	v_cvt_pk_bf16_f32 v20, v16, v17
	v_cvt_pk_bf16_f32 v21, v18, v19
	global_store_dwordx2 v[68:69], v[20:21], off
	s_waitcnt vmcnt(40)
	v_lshlrev_b32_e32 v20, 16, v76
	v_and_b32_e32 v21, 0xffff0000, v76
	v_lshlrev_b32_e32 v22, 16, v77
	v_and_b32_e32 v23, 0xffff0000, v77
	s_waitcnt vmcnt(32)
	v_pk_fma_f32 v[18:19], v[94:95], v[18:19], v[22:23] op_sel_hi:[0,1,1]
	v_pk_fma_f32 v[16:17], v[94:95], v[16:17], v[20:21] op_sel_hi:[0,1,1]
	v_cvt_pk_bf16_f32 v20, v16, v17
	v_cvt_pk_bf16_f32 v21, v18, v19
	global_store_dwordx2 v[70:71], v[20:21], off
	v_lshlrev_b32_e32 v20, 16, v78
	v_and_b32_e32 v21, 0xffff0000, v78
	v_lshlrev_b32_e32 v22, 16, v79
	v_and_b32_e32 v23, 0xffff0000, v79
	s_waitcnt vmcnt(32)
	v_pk_fma_f32 v[18:19], v[96:97], v[18:19], v[22:23] op_sel_hi:[0,1,1]
	v_pk_fma_f32 v[16:17], v[96:97], v[16:17], v[20:21] op_sel_hi:[0,1,1]
	v_cvt_pk_bf16_f32 v20, v16, v17
	v_cvt_pk_bf16_f32 v21, v18, v19
	global_store_dwordx2 v[72:73], v[20:21], off
	v_lshlrev_b32_e32 v20, 16, v80
	v_and_b32_e32 v21, 0xffff0000, v80
	v_lshlrev_b32_e32 v22, 16, v81
	v_and_b32_e32 v23, 0xffff0000, v81
	s_waitcnt vmcnt(32)
	v_pk_fma_f32 v[18:19], v[98:99], v[18:19], v[22:23] op_sel_hi:[0,1,1]
	v_pk_fma_f32 v[16:17], v[98:99], v[16:17], v[20:21] op_sel_hi:[0,1,1]
	v_cvt_pk_bf16_f32 v20, v16, v17
	v_cvt_pk_bf16_f32 v21, v18, v19
	global_store_dwordx2 v[74:75], v[20:21], off
	v_lshlrev_b32_e32 v20, 16, v82
	v_and_b32_e32 v21, 0xffff0000, v82
	v_lshlrev_b32_e32 v22, 16, v83
	v_and_b32_e32 v23, 0xffff0000, v83
	s_waitcnt vmcnt(32)
	v_pk_fma_f32 v[18:19], v[100:101], v[18:19], v[22:23] op_sel_hi:[0,1,1]
	v_pk_fma_f32 v[16:17], v[100:101], v[16:17], v[20:21] op_sel_hi:[0,1,1]
	v_cvt_pk_bf16_f32 v20, v16, v17
	v_cvt_pk_bf16_f32 v21, v18, v19
	global_store_dwordx2 v[84:85], v[20:21], off
	v_lshlrev_b32_e32 v20, 16, v88
	v_and_b32_e32 v21, 0xffff0000, v88
	v_lshlrev_b32_e32 v22, 16, v89
	v_and_b32_e32 v23, 0xffff0000, v89
	s_waitcnt vmcnt(32)
	v_pk_fma_f32 v[18:19], v[102:103], v[18:19], v[22:23] op_sel_hi:[0,1,1]
	v_pk_fma_f32 v[16:17], v[102:103], v[16:17], v[20:21] op_sel_hi:[0,1,1]
	v_cvt_pk_bf16_f32 v20, v16, v17
	v_cvt_pk_bf16_f32 v21, v18, v19
	global_store_dwordx2 v[86:87], v[20:21], off
	v_lshlrev_b32_e32 v20, 16, v90
	v_and_b32_e32 v21, 0xffff0000, v90
	v_lshlrev_b32_e32 v22, 16, v91
	v_and_b32_e32 v23, 0xffff0000, v91
	s_waitcnt vmcnt(32)
	v_pk_fma_f32 v[18:19], v[104:105], v[18:19], v[22:23] op_sel_hi:[0,1,1]
	v_pk_fma_f32 v[16:17], v[104:105], v[16:17], v[20:21] op_sel_hi:[0,1,1]
	v_cvt_pk_bf16_f32 v20, v16, v17
	v_cvt_pk_bf16_f32 v21, v18, v19
	global_store_dwordx2 v[14:15], v[20:21], off
	v_lshlrev_b32_e32 v14, 16, v92
	v_and_b32_e32 v15, 0xffff0000, v92
	v_lshlrev_b32_e32 v20, 16, v93
	v_and_b32_e32 v21, 0xffff0000, v93
	s_waitcnt vmcnt(32)
	v_pk_fma_f32 v[18:19], v[106:107], v[18:19], v[20:21] op_sel_hi:[0,1,1]
	v_pk_fma_f32 v[14:15], v[106:107], v[16:17], v[14:15] op_sel_hi:[0,1,1]
	v_cvt_pk_bf16_f32 v16, v14, v15
	v_cvt_pk_bf16_f32 v17, v18, v19
	global_store_dwordx2 v[10:11], v[16:17], off
	v_lshlrev_b32_e32 v16, 16, v12
	v_and_b32_e32 v17, 0xffff0000, v12
	v_lshlrev_b32_e32 v12, 16, v13
	v_and_b32_e32 v13, 0xffff0000, v13
	s_waitcnt vmcnt(32)
	v_pk_fma_f32 v[18:19], v[0:1], v[18:19], v[12:13] op_sel_hi:[0,1,1]
	v_pk_fma_f32 v[16:17], v[0:1], v[14:15], v[16:17] op_sel_hi:[0,1,1]
	v_lshl_add_u64 v[10:11], v[10:11], 0, s[90:91]
	s_cbranch_scc0 .LBB0_1249
	s_branch .LBB0_1238
